# attention tile loop: first-half V transposed LDS reads issued in the MFMA-to-VALU wait slot instead of s_nop
# speedup vs baseline: 1.0048x; 1.0048x over previous
; #define LAS __attribute__((address_space(3)))
; DI unsigned pk2(float lo, float hi) { f32x2 v = {lo, hi}; bfv2 b = __builtin_convertvector(v, bfv2); return __builtin_bit_cast(unsigned, b); }
; DI f32x16 mfma32(bf16x8 a, bf16x8 b, f32x16 c) { return __builtin_amdgcn_mfma_f32_32x32x16_bf16(a, b, c, 0, 0, 0); }
; DI void attn_unit(const Params& p, int unit, unsigned char* lds) {
;     ...
;   for (int tl = 0; tl < 64; ++tl) {
;     { const int tn_ = tl + 1 < 64 ? tl + 1 : 63; AT_LOAD(tn_); }
;     asm volatile("" ::: "memory"); __builtin_amdgcn_sched_barrier(0);
;     const bf16_t* k_ = Ks + (tl & 1) * 64 * 72; const bf16_t* v_ = Vs + (tl & 1) * 64 * 72;
; #pragma unroll
;     for (int kt = 0; kt < 2; ++kt) {
;       f32x16 Sx[2];
;       f32x16 zero16;
; #pragma unroll
;       for (int i = 0; i < 16; ++i) zero16[i] = 0.f;
; #pragma unroll
;       for (int ks = 0; ks < 4; ++ks) {
;         const bf16x8 kf = *(const bf16x8*)(k_ + (32 * kt + r) * 72 + 16 * ks + 8 * hh);
; #pragma unroll
;         for (int g = 0; g < 2; ++g) Sx[g] = mfma32(kf, Qf[g][ks], ks == 0 ? zero16 : Sx[g]);
;       }
;       bf16x8 vf[2][2];
; #pragma unroll
;       for (int s = 0; s < 2; ++s)
; #pragma unroll
;         for (int dt = 0; dt < 2; ++dt) {
;           const bf16_t* vb_ = v_ + (32 * kt + 16 * s) * 72 + 32 * dt + troff;
;           const s16x4 lo = __builtin_amdgcn_ds_read_tr16_b64_v4i16((LAS s16x4*)(vb_));
;           const s16x4 hi = __builtin_amdgcn_ds_read_tr16_b64_v4i16((LAS s16x4*)(vb_ + 8 * 72));
;           vf[s][dt] = __builtin_shufflevector(lo, hi, 0, 1, 2, 3, 4, 5, 6, 7);
;         }
; #pragma unroll
;       for (int g = 0; g < 2; ++g) {
;         float pv[16];
; #pragma unroll
;         for (int i = 0; i < 16; ++i) { pv[i] = __builtin_amdgcn_exp2f(Sx[g][i]); lsum[g] += pv[i]; }
;         bf16x8 Pb[2];
; #pragma unroll
;         for (int s = 0; s < 2; ++s) {
;           const u32x4 w = {pk2(pv[8 * s], pv[8 * s + 1]), pk2(pv[8 * s + 2], pv[8 * s + 3]), pk2(pv[8 * s + 4], pv[8 * s + 5]), pk2(pv[8 * s + 6], pv[8 * s + 7])};
;           Pb[s] = __builtin_bit_cast(bf16x8, w);
;         }
; #pragma unroll
;         for (int s = 0; s < 2; ++s)
; #pragma unroll
;           for (int dt = 0; dt < 2; ++dt) O[dt][g] = mfma32(vf[s][dt], Pb[s], O[dt][g]);
;       }
;     }
.LBB0_99:
	s_add_i32 s5, s4, 64
	global_load_dwordx4 v[128:131], v[238:239], off
	global_load_dwordx4 v[132:135], v[238:239], off offset:256
	global_load_dwordx4 v[136:139], v[240:241], off
	global_load_dwordx4 v[140:143], v[240:241], off offset:256
	v_lshl_add_u64 v[238:239], v[238:239], 0, s[6:7]
	v_lshl_add_u64 v[240:241], v[240:241], 0, s[6:7]
	s_and_b32 s2, s4, 64
	s_mulk_i32 s2, 0x90
	v_add_u32_e32 v205, s2, v160
	ds_read_b128 v[64:67], v205
	ds_read_b128 v[144:147], v205 offset:32
	v_add_u32_e32 v153, s2, v165
	s_and_b32 s2, s5, 64
	s_mulk_i32 s2, 0x90
	s_waitcnt lgkmcnt(1)
	v_mfma_f32_32x32x16_bf16 v[80:95], v[64:67], v[116:119], 0
	s_cmpk_eq_i32 s5, 0xfc0
	s_mov_b32 s4, s5
	v_mfma_f32_32x32x16_bf16 v[64:79], v[64:67], v[124:127], 0
	s_waitcnt lgkmcnt(0)
	v_mfma_f32_32x32x16_bf16 v[80:95], v[144:147], v[108:111], v[80:95]
	v_mfma_f32_32x32x16_bf16 v[64:79], v[144:147], v[120:123], v[64:79]
	ds_read_b128 v[144:147], v205 offset:64
	s_waitcnt lgkmcnt(0)
	v_mfma_f32_32x32x16_bf16 v[80:95], v[144:147], v[100:103], v[80:95]
	v_mfma_f32_32x32x16_bf16 v[64:79], v[144:147], v[112:115], v[64:79]
	ds_read_b128 v[144:147], v205 offset:96
	s_waitcnt lgkmcnt(0)
	v_mfma_f32_32x32x16_bf16 v[80:95], v[144:147], v[96:99], v[80:95]
	v_mfma_f32_32x32x16_bf16 v[64:79], v[144:147], v[104:107], v[64:79]
	ds_read_b64_tr_b16 v[206:207], v153 offset:18432
	ds_read_b64_tr_b16 v[208:209], v153 offset:19584
	ds_read_b64_tr_b16 v[210:211], v153 offset:18496
	ds_read_b64_tr_b16 v[212:213], v153 offset:19648
	ds_read_b64_tr_b16 v[144:145], v153 offset:20736
	ds_read_b64_tr_b16 v[146:147], v153 offset:21888
	ds_read_b64_tr_b16 v[148:149], v153 offset:20800
	ds_read_b64_tr_b16 v[150:151], v153 offset:21952
	s_nop 2
	v_exp_f32_e32 v157, v80
	v_exp_f32_e32 v81, v81
	v_exp_f32_e32 v215, v82
	v_exp_f32_e32 v83, v83
	v_exp_f32_e32 v217, v84
	v_exp_f32_e32 v85, v85
	v_exp_f32_e32 v219, v86
	v_exp_f32_e32 v87, v87
	v_exp_f32_e32 v156, v64
	v_exp_f32_e32 v80, v65
	v_exp_f32_e32 v214, v66
	v_exp_f32_e32 v82, v67
	v_cvt_pk_bf16_f32 v64, v157, v81
	v_cvt_pk_bf16_f32 v65, v215, v83
	v_cvt_pk_bf16_f32 v66, v217, v85
	v_cvt_pk_bf16_f32 v67, v219, v87
	v_exp_f32_e32 v216, v68
	v_exp_f32_e32 v84, v69
	s_waitcnt lgkmcnt(6)
	v_mfma_f32_32x32x16_bf16 v[48:63], v[206:209], v[64:67], v[48:63]
	v_exp_f32_e32 v218, v70
	v_exp_f32_e32 v86, v71
	v_exp_f32_e32 v221, v88
	v_exp_f32_e32 v220, v72
	v_exp_f32_e32 v89, v89
	v_exp_f32_e32 v88, v73
	v_exp_f32_e32 v159, v90
	s_waitcnt lgkmcnt(4)
	v_mfma_f32_32x32x16_bf16 v[32:47], v[210:213], v[64:67], v[32:47]
	v_add_f32_e64 v64, v154, v156
	v_add_f32_e64 v65, v155, v157
	v_cvt_pk_bf16_f32 v66, v216, v84
	v_add_f32_e64 v64, v80, v64
	v_add_f32_e64 v65, v81, v65
	v_cvt_pk_bf16_f32 v67, v218, v86
	v_add_f32_e32 v64, v214, v64
	v_add_f32_e32 v65, v215, v65
	v_exp_f32_e32 v171, v91
	v_add_f32_e32 v64, v82, v64
	v_add_f32_e32 v65, v83, v65
	v_exp_f32_e32 v169, v92
	v_add_f32_e32 v64, v216, v64
	v_add_f32_e32 v65, v217, v65
	v_exp_f32_e32 v175, v93
	v_add_f32_e32 v64, v84, v64
	v_add_f32_e32 v65, v85, v65
	v_exp_f32_e32 v173, v94
	v_add_f32_e32 v64, v218, v64
	v_add_f32_e32 v65, v219, v65
	v_exp_f32_e32 v177, v95
	v_add_f32_e32 v64, v86, v64
	v_add_f32_e32 v65, v87, v65
	v_cvt_pk_bf16_f32 v152, v221, v89
	v_add_f32_e32 v64, v220, v64
	v_add_f32_e32 v65, v221, v65
	v_exp_f32_e32 v158, v74
	v_add_f32_e32 v178, v88, v64
	v_add_f32_e32 v179, v89, v65
	v_cvt_pk_bf16_f32 v64, v156, v80
	v_cvt_pk_bf16_f32 v65, v214, v82
	v_exp_f32_e32 v170, v75
	v_exp_f32_e32 v168, v76
	v_mfma_f32_32x32x16_bf16 v[16:31], v[206:209], v[64:67], v[16:31]
	ds_read_b128 v[206:209], v205 offset:4640
	v_exp_f32_e32 v174, v77
	v_exp_f32_e32 v172, v78
	v_exp_f32_e32 v176, v79
	v_cvt_pk_bf16_f32 v156, v220, v88
	v_cvt_pk_bf16_f32 v154, v169, v175
	v_cvt_pk_bf16_f32 v155, v173, v177
	v_mfma_f32_32x32x16_bf16 v[0:15], v[210:213], v[64:67], v[0:15]
	ds_read_b128 v[64:67], v205 offset:4608
	v_cvt_pk_bf16_f32 v157, v158, v170
	s_waitcnt lgkmcnt(0)
	v_mfma_f32_32x32x16_bf16 v[80:95], v[64:67], v[116:119], 0
	v_mfma_f32_32x32x16_bf16 v[64:79], v[64:67], v[124:127], 0
	v_mfma_f32_32x32x16_bf16 v[80:95], v[206:209], v[108:111], v[80:95]
	v_mfma_f32_32x32x16_bf16 v[64:79], v[206:209], v[120:123], v[64:79]
	ds_read_b128 v[206:209], v205 offset:4672
	s_waitcnt lgkmcnt(0)
	v_mfma_f32_32x32x16_bf16 v[80:95], v[206:209], v[100:103], v[80:95]
	v_mfma_f32_32x32x16_bf16 v[64:79], v[206:209], v[112:115], v[64:79]
	ds_read_b128 v[206:209], v205 offset:4704
	s_waitcnt lgkmcnt(0)
; #define LAS __attribute__((address_space(3)))
; DI unsigned pk2(float lo, float hi) { f32x2 v = {lo, hi}; bfv2 b = __builtin_convertvector(v, bfv2); return __builtin_bit_cast(unsigned, b); }
; DI f32x16 mfma32(bf16x8 a, bf16x8 b, f32x16 c) { return __builtin_amdgcn_mfma_f32_32x32x16_bf16(a, b, c, 0, 0, 0); }
; #define AT_STORE(buf_) do { _Pragma("unroll") for (int i_ = 0; i_ < 2; ++i_) { *(u32x4*)(Ks + (buf_) * 64 * 72 + (skey + 32 * i_) * 72 + sdc) = rk[i_]; \
;     *(u32x4*)(Vs + (buf_) * 64 * 72 + (skey + 32 * i_) * 72 + sdc) = rv[i_]; } } while (0)
; DI void attn_unit(const Params& p, int unit, unsigned char* lds) {
;     ...
;       for (int ks = 0; ks < 4; ++ks) {
;         const bf16x8 kf = *(const bf16x8*)(k_ + (32 * kt + r) * 72 + 16 * ks + 8 * hh);
; #pragma unroll
;         for (int g = 0; g < 2; ++g) Sx[g] = mfma32(kf, Qf[g][ks], ks == 0 ? zero16 : Sx[g]);
;       }
;       bf16x8 vf[2][2];
; #pragma unroll
;       for (int s = 0; s < 2; ++s)
; #pragma unroll
;         for (int dt = 0; dt < 2; ++dt) {
;           const bf16_t* vb_ = v_ + (32 * kt + 16 * s) * 72 + 32 * dt + troff;
;           const s16x4 lo = __builtin_amdgcn_ds_read_tr16_b64_v4i16((LAS s16x4*)(vb_));
;           const s16x4 hi = __builtin_amdgcn_ds_read_tr16_b64_v4i16((LAS s16x4*)(vb_ + 8 * 72));
;           vf[s][dt] = __builtin_shufflevector(lo, hi, 0, 1, 2, 3, 4, 5, 6, 7);
;         }
; #pragma unroll
;       for (int g = 0; g < 2; ++g) {
;         float pv[16];
; #pragma unroll
;         for (int i = 0; i < 16; ++i) { pv[i] = __builtin_amdgcn_exp2f(Sx[g][i]); lsum[g] += pv[i]; }
;         bf16x8 Pb[2];
; #pragma unroll
;         for (int s = 0; s < 2; ++s) {
;           const u32x4 w = {pk2(pv[8 * s], pv[8 * s + 1]), pk2(pv[8 * s + 2], pv[8 * s + 3]), pk2(pv[8 * s + 4], pv[8 * s + 5]), pk2(pv[8 * s + 6], pv[8 * s + 7])};
;           Pb[s] = __builtin_bit_cast(bf16x8, w);
;         }
; #pragma unroll
;         for (int s = 0; s < 2; ++s)
; #pragma unroll
;           for (int dt = 0; dt < 2; ++dt) O[dt][g] = mfma32(vf[s][dt], Pb[s], O[dt][g]);
;       }
;     }
;     if (tl + 1 < 64) AT_STORE((tl + 1) & 1);
;     __syncthreads();
	v_mfma_f32_32x32x16_bf16 v[80:95], v[206:209], v[96:99], v[80:95]
	v_mfma_f32_32x32x16_bf16 v[64:79], v[206:209], v[104:107], v[64:79]
	s_nop 10
	v_exp_f32_e32 v223, v80
	v_exp_f32_e32 v81, v81
	ds_read_b64_tr_b16 v[206:207], v153 offset:23040
	ds_read_b64_tr_b16 v[208:209], v153 offset:24192
	ds_read_b64_tr_b16 v[210:211], v153 offset:23104
	ds_read_b64_tr_b16 v[212:213], v153 offset:24256
	ds_read_b64_tr_b16 v[214:215], v153 offset:25344
	ds_read_b64_tr_b16 v[216:217], v153 offset:26496
	ds_read_b64_tr_b16 v[218:219], v153 offset:25408
	ds_read_b64_tr_b16 v[220:221], v153 offset:26560
	v_exp_f32_e32 v225, v82
	v_cvt_pk_bf16_f32 v153, v159, v171
	v_exp_f32_e32 v83, v83
	v_exp_f32_e32 v227, v84
	v_exp_f32_e32 v222, v64
	v_exp_f32_e32 v80, v65
	v_add_f32_e32 v64, v158, v178
	v_add_f32_e32 v65, v159, v179
	v_exp_f32_e32 v224, v66
	v_add_f32_e32 v64, v170, v64
	v_add_f32_e32 v65, v171, v65
	v_exp_f32_e32 v82, v67
	v_add_f32_e32 v64, v168, v64
	v_add_f32_e32 v65, v169, v65
	v_mfma_f32_32x32x16_bf16 v[48:63], v[144:147], v[152:155], v[48:63]
	v_add_f32_e64 v64, v174, v64
	v_add_f32_e64 v65, v175, v65
	v_cvt_pk_bf16_f32 v158, v168, v174
	v_add_f32_e64 v64, v172, v64
	v_add_f32_e64 v65, v173, v65
	v_cvt_pk_bf16_f32 v159, v172, v176
	v_exp_f32_e32 v226, v68
	v_exp_f32_e32 v85, v85
	v_exp_f32_e32 v84, v69
	v_mfma_f32_32x32x16_bf16 v[32:47], v[148:151], v[152:155], v[32:47]
	v_add_f32_e64 v152, v176, v64
	v_add_f32_e64 v153, v177, v65
	v_exp_f32_e32 v229, v86
	v_exp_f32_e32 v87, v87
	v_exp_f32_e32 v228, v70
	v_exp_f32_e32 v86, v71
	v_exp_f32_e32 v231, v88
	v_exp_f32_e32 v230, v72
	v_mfma_f32_32x32x16_bf16 v[16:31], v[144:147], v[156:159], v[16:31]
	v_add_f32_e64 v144, v152, v222
	v_add_f32_e64 v145, v153, v223
	v_exp_f32_e32 v89, v89
	v_add_f32_e32 v144, v80, v144
	v_add_f32_e32 v145, v81, v145
	v_exp_f32_e32 v88, v73
	v_add_f32_e32 v144, v224, v144
	v_add_f32_e32 v145, v225, v145
	v_exp_f32_e32 v233, v90
	v_add_f32_e32 v144, v82, v144
	v_add_f32_e32 v145, v83, v145
	v_mfma_f32_32x32x16_bf16 v[0:15], v[148:151], v[156:159], v[0:15]
	v_add_f32_e64 v144, v226, v144
	v_add_f32_e64 v145, v227, v145
	v_cvt_pk_bf16_f32 v64, v223, v81
	v_add_f32_e64 v68, v84, v144
	v_add_f32_e64 v69, v85, v145
	v_cvt_pk_bf16_f32 v65, v225, v83
	v_cvt_pk_bf16_f32 v66, v227, v85
	v_exp_f32_e32 v232, v74
	v_add_f32_e32 v68, v228, v68
	v_add_f32_e32 v69, v229, v69
	v_cvt_pk_bf16_f32 v67, v229, v87
	v_exp_f32_e32 v91, v91
	v_exp_f32_e32 v90, v75
	v_add_f32_e32 v68, v86, v68
	v_add_f32_e32 v69, v87, v69
	s_waitcnt lgkmcnt(6)
	v_mfma_f32_32x32x16_bf16 v[48:63], v[206:209], v[64:67], v[48:63]
	v_exp_f32_e32 v235, v92
	v_exp_f32_e32 v234, v76
	v_add_f32_e32 v68, v230, v68
	v_add_f32_e32 v69, v231, v69
	v_exp_f32_e32 v93, v93
	v_exp_f32_e32 v92, v77
	v_add_f32_e32 v68, v88, v68
	v_add_f32_e32 v69, v89, v69
	v_exp_f32_e32 v237, v94
	s_waitcnt lgkmcnt(4)
	v_mfma_f32_32x32x16_bf16 v[32:47], v[210:213], v[64:67], v[32:47]
	v_cvt_pk_bf16_f32 v64, v222, v80
	v_cvt_pk_bf16_f32 v65, v224, v82
	v_cvt_pk_bf16_f32 v66, v226, v84
	v_cvt_pk_bf16_f32 v67, v228, v86
	v_exp_f32_e32 v95, v95
	v_exp_f32_e32 v236, v78
	v_add_f32_e32 v68, v232, v68
	v_add_f32_e32 v69, v233, v69
	v_mfma_f32_32x32x16_bf16 v[16:31], v[206:209], v[64:67], v[16:31]
	v_exp_f32_e32 v94, v79
	v_add_f32_e32 v68, v90, v68
	v_add_f32_e32 v69, v91, v69
	v_cvt_pk_bf16_f32 v70, v235, v93
	v_add_f32_e32 v68, v234, v68
	v_add_f32_e32 v69, v235, v69
	v_cvt_pk_bf16_f32 v71, v237, v95
	v_add_f32_e32 v68, v92, v68
	v_add_f32_e32 v69, v93, v69
	v_mfma_f32_32x32x16_bf16 v[0:15], v[210:213], v[64:67], v[0:15]
	v_add_f32_e64 v72, v236, v68
	v_add_f32_e64 v73, v237, v69
	v_cvt_pk_bf16_f32 v68, v231, v89
	v_cvt_pk_bf16_f32 v69, v233, v91
	v_add_f32_e64 v154, v94, v72
	v_add_f32_e64 v155, v95, v73
	v_add_u32_e32 v64, s2, v204
	s_waitcnt vmcnt(3)
	ds_write_b128 v64, v[128:131]
	s_waitcnt vmcnt(2)
	ds_write_b128 v64, v[132:135] offset:18432
	s_waitcnt vmcnt(1)
	ds_write_b128 v64, v[136:139] offset:4608
	s_waitcnt vmcnt(0)
	ds_write_b128 v64, v[140:143] offset:23040
	s_waitcnt lgkmcnt(0)
	v_mfma_f32_32x32x16_bf16 v[48:63], v[214:217], v[68:71], v[48:63]
	s_barrier
	v_mfma_f32_32x32x16_bf16 v[32:47], v[218:221], v[68:71], v[32:47]
	v_cvt_pk_bf16_f32 v68, v230, v88
	v_cvt_pk_bf16_f32 v69, v232, v90
	v_cvt_pk_bf16_f32 v70, v234, v92
	v_cvt_pk_bf16_f32 v71, v236, v94
	s_nop 1
	v_mfma_f32_32x32x16_bf16 v[16:31], v[214:217], v[68:71], v[16:31]
	v_mfma_f32_32x32x16_bf16 v[0:15], v[218:221], v[68:71], v[0:15]
	s_cbranch_scc0 .LBB0_99
; #define LAS __attribute__((address_space(3)))
; DI unsigned pk2(float lo, float hi) { f32x2 v = {lo, hi}; bfv2 b = __builtin_convertvector(v, bfv2); return __builtin_bit_cast(unsigned, b); }
; DI void attn_unit(const Params& p, int unit, unsigned char* lds) {
;     ...
;   for (int tl = 0; tl < 64; ++tl) {
;     { const int tn_ = tl + 1 < 64 ? tl + 1 : 63; AT_LOAD(tn_); }
;     asm volatile("" ::: "memory"); __builtin_amdgcn_sched_barrier(0);
;     const bf16_t* k_ = Ks + (tl & 1) * 64 * 72; const bf16_t* v_ = Vs + (tl & 1) * 64 * 72;
; #pragma unroll
;     for (int kt = 0; kt < 2; ++kt) {
;       f32x16 Sx[2];
;       f32x16 zero16;
; #pragma unroll
;       for (int i = 0; i < 16; ++i) zero16[i] = 0.f;
; #pragma unroll
;       for (int ks = 0; ks < 4; ++ks) {
;         const bf16x8 kf = *(const bf16x8*)(k_ + (32 * kt + r) * 72 + 16 * ks + 8 * hh);
; #pragma unroll
;         for (int g = 0; g < 2; ++g) Sx[g] = mfma32(kf, Qf[g][ks], ks == 0 ? zero16 : Sx[g]);
;       }
;       bf16x8 vf[2][2];
; #pragma unroll
;       for (int s = 0; s < 2; ++s)
; #pragma unroll
;         for (int dt = 0; dt < 2; ++dt) {
;           const bf16_t* vb_ = v_ + (32 * kt + 16 * s) * 72 + 32 * dt + troff;
;           const s16x4 lo = __builtin_amdgcn_ds_read_tr16_b64_v4i16((LAS s16x4*)(vb_));
;           const s16x4 hi = __builtin_amdgcn_ds_read_tr16_b64_v4i16((LAS s16x4*)(vb_ + 8 * 72));
;           vf[s][dt] = __builtin_shufflevector(lo, hi, 0, 1, 2, 3, 4, 5, 6, 7);
;         }
; #pragma unroll
;       for (int g = 0; g < 2; ++g) {
;         float pv[16];
; #pragma unroll
;         for (int i = 0; i < 16; ++i) { pv[i] = __builtin_amdgcn_exp2f(Sx[g][i]); lsum[g] += pv[i]; }
;         bf16x8 Pb[2];
; #pragma unroll
;         for (int s = 0; s < 2; ++s) {
;           const u32x4 w = {pk2(pv[8 * s], pv[8 * s + 1]), pk2(pv[8 * s + 2], pv[8 * s + 3]), pk2(pv[8 * s + 4], pv[8 * s + 5]), pk2(pv[8 * s + 6], pv[8 * s + 7])};
;           Pb[s] = __builtin_bit_cast(bf16x8, w);
;         }
; #pragma unroll
;         for (int s = 0; s < 2; ++s)
; #pragma unroll
;           for (int dt = 0; dt < 2; ++dt) O[dt][g] = mfma32(vf[s][dt], Pb[s], O[dt][g]);
;       }
;     }
;     if (tl + 1 < 64) AT_STORE((tl + 1) & 1);
;     __syncthreads();
;   }
;     ...
;   const int pcol = kvc == 0 ? A_V : (kvc == 1 ? A_Z : (kvc == 2 ? B_V : D_X));
	ds_read_b128 v[64:67], v160 offset:9216
	ds_read_b128 v[128:131], v160 offset:9248
	s_cmp_lt_i32 s34, 1
	s_mov_b64 s[8:9], 0x100
	s_waitcnt lgkmcnt(1)
	v_mfma_f32_32x32x16_bf16 v[80:95], v[64:67], v[116:119], 0
	v_mfma_f32_32x32x16_bf16 v[64:79], v[64:67], v[124:127], 0
	s_waitcnt lgkmcnt(0)
	v_mfma_f32_32x32x16_bf16 v[80:95], v[128:131], v[108:111], v[80:95]
	v_mfma_f32_32x32x16_bf16 v[64:79], v[128:131], v[120:123], v[64:79]
	ds_read_b128 v[128:131], v160 offset:9280
	s_waitcnt lgkmcnt(0)
	v_mfma_f32_32x32x16_bf16 v[80:95], v[128:131], v[100:103], v[80:95]
	v_mfma_f32_32x32x16_bf16 v[64:79], v[128:131], v[112:115], v[64:79]
	ds_read_b128 v[128:131], v160 offset:9312
	ds_read_b64_tr_b16 v[168:169], v165 offset:27648
	ds_read_b64_tr_b16 v[170:171], v165 offset:28800
	ds_read_b64_tr_b16 v[172:173], v165 offset:27712
	ds_read_b64_tr_b16 v[174:175], v165 offset:28864
	ds_read_b64_tr_b16 v[176:177], v165 offset:29952
	ds_read_b64_tr_b16 v[178:179], v165 offset:31104
	ds_read_b64_tr_b16 v[204:205], v165 offset:30016
	ds_read_b64_tr_b16 v[206:207], v165 offset:31168
	s_waitcnt lgkmcnt(8)
	v_mfma_f32_32x32x16_bf16 v[64:79], v[128:131], v[104:107], v[64:79]
	v_mfma_f32_32x32x16_bf16 v[80:95], v[128:131], v[96:99], v[80:95]
	s_nop 10
	v_exp_f32_e32 v128, v64
	v_exp_f32_e32 v129, v65
	v_exp_f32_e32 v130, v66
	v_exp_f32_e32 v131, v67
	v_exp_f32_e32 v132, v68
	v_exp_f32_e32 v133, v69
	v_exp_f32_e32 v134, v70
	v_exp_f32_e32 v135, v71
	v_exp_f32_e32 v144, v80
	v_exp_f32_e32 v145, v81
	v_exp_f32_e32 v146, v82
	v_exp_f32_e32 v147, v83
	v_exp_f32_e32 v148, v84
	v_exp_f32_e32 v149, v85
	v_exp_f32_e32 v150, v86
	v_exp_f32_e32 v151, v87
	v_cvt_pk_bf16_f32 v64, v128, v129
	v_cvt_pk_bf16_f32 v65, v130, v131
	v_cvt_pk_bf16_f32 v66, v132, v133
	v_cvt_pk_bf16_f32 v67, v134, v135
	v_cvt_pk_bf16_f32 v80, v144, v145
	v_cvt_pk_bf16_f32 v81, v146, v147
	v_cvt_pk_bf16_f32 v82, v148, v149
	v_cvt_pk_bf16_f32 v83, v150, v151
	s_waitcnt lgkmcnt(6)
	v_mfma_f32_32x32x16_bf16 v[16:31], v[168:171], v[64:67], v[16:31]
	v_exp_f32_e32 v152, v88
	v_exp_f32_e32 v153, v89
	v_exp_f32_e32 v156, v90
	v_exp_f32_e32 v157, v91
	v_exp_f32_e32 v158, v92
	v_exp_f32_e32 v159, v93
	v_exp_f32_e32 v166, v94
	s_waitcnt lgkmcnt(4)
	v_mfma_f32_32x32x16_bf16 v[0:15], v[172:175], v[64:67], v[0:15]
	ds_read_b128 v[64:67], v160 offset:13824
	v_exp_f32_e32 v167, v95
	v_cvt_pk_bf16_f32 v84, v152, v153
	v_cvt_pk_bf16_f32 v85, v156, v157
	v_cvt_pk_bf16_f32 v86, v158, v159
	v_cvt_pk_bf16_f32 v87, v166, v167
	v_exp_f32_e32 v136, v72
	v_mfma_f32_32x32x16_bf16 v[48:63], v[168:171], v[80:83], v[48:63]
	v_exp_f32_e32 v137, v73
	v_exp_f32_e32 v138, v74
	v_exp_f32_e32 v139, v75
	v_exp_f32_e32 v140, v76
	v_exp_f32_e32 v141, v77
	v_exp_f32_e32 v142, v78
	v_exp_f32_e32 v143, v79
	v_mfma_f32_32x32x16_bf16 v[32:47], v[172:175], v[80:83], v[32:47]
	v_cvt_pk_bf16_f32 v68, v136, v137
	v_cvt_pk_bf16_f32 v69, v138, v139
	v_cvt_pk_bf16_f32 v70, v140, v141
	v_cvt_pk_bf16_f32 v71, v142, v143
	s_waitcnt lgkmcnt(3)
	v_mfma_f32_32x32x16_bf16 v[48:63], v[176:179], v[84:87], v[48:63]
	s_waitcnt lgkmcnt(1)
	v_mfma_f32_32x32x16_bf16 v[32:47], v[204:207], v[84:87], v[32:47]
	s_waitcnt lgkmcnt(0)
	v_mfma_f32_32x32x16_bf16 v[80:95], v[64:67], v[116:119], 0
	ds_read_b128 v[116:119], v160 offset:13856
	v_mfma_f32_32x32x16_bf16 v[16:31], v[176:179], v[68:71], v[16:31]
	v_mfma_f32_32x32x16_bf16 v[0:15], v[204:207], v[68:71], v[0:15]
	v_mfma_f32_32x32x16_bf16 v[64:79], v[64:67], v[124:127], 0
	s_waitcnt lgkmcnt(0)
	v_mfma_f32_32x32x16_bf16 v[80:95], v[116:119], v[108:111], v[80:95]
	ds_read_b128 v[108:111], v160 offset:13888
	v_mfma_f32_32x32x16_bf16 v[64:79], v[116:119], v[120:123], v[64:79]
	s_waitcnt lgkmcnt(0)
	v_mfma_f32_32x32x16_bf16 v[80:95], v[108:111], v[100:103], v[80:95]
	ds_read_b128 v[100:103], v160 offset:13920
	v_mfma_f32_32x32x16_bf16 v[64:79], v[108:111], v[112:115], v[64:79]
	s_waitcnt lgkmcnt(0)
	v_mfma_f32_32x32x16_bf16 v[80:95], v[100:103], v[96:99], v[80:95]
	v_mfma_f32_32x32x16_bf16 v[64:79], v[100:103], v[104:107], v[64:79]
	s_nop 10
	v_exp_f32_e32 v80, v80
	v_exp_f32_e32 v81, v81
	v_exp_f32_e32 v82, v82
	v_exp_f32_e32 v83, v83
	v_exp_f32_e32 v84, v84
	v_exp_f32_e32 v85, v85
	v_exp_f32_e32 v86, v86
	v_exp_f32_e32 v87, v87
	ds_read_b64_tr_b16 v[108:109], v165 offset:32256
	ds_read_b64_tr_b16 v[110:111], v165 offset:33408
	ds_read_b64_tr_b16 v[104:105], v165 offset:32320
	ds_read_b64_tr_b16 v[106:107], v165 offset:33472
	ds_read_b64_tr_b16 v[96:97], v165 offset:34560
	ds_read_b64_tr_b16 v[98:99], v165 offset:35712
	ds_read_b64_tr_b16 v[100:101], v165 offset:34624
	ds_read_b64_tr_b16 v[102:103], v165 offset:35776
	v_cvt_pk_bf16_f32 v112, v80, v81
	v_cvt_pk_bf16_f32 v113, v82, v83
	v_cvt_pk_bf16_f32 v114, v84, v85
	v_cvt_pk_bf16_f32 v115, v86, v87
	v_exp_f32_e32 v68, v68
	v_exp_f32_e32 v69, v69
	s_waitcnt lgkmcnt(6)
	v_mfma_f32_32x32x16_bf16 v[48:63], v[108:111], v[112:115], v[48:63]
	v_exp_f32_e32 v70, v70
	v_exp_f32_e32 v71, v71
	v_exp_f32_e32 v88, v88
	v_exp_f32_e32 v89, v89
	v_exp_f32_e32 v90, v90
	v_exp_f32_e32 v91, v91
	v_exp_f32_e32 v92, v92
	s_waitcnt lgkmcnt(4)
	v_mfma_f32_32x32x16_bf16 v[32:47], v[104:107], v[112:115], v[32:47]
	v_exp_f32_e32 v112, v64
	v_exp_f32_e32 v113, v65
	v_exp_f32_e32 v114, v66
	v_exp_f32_e32 v115, v67
	v_cvt_pk_bf16_f32 v66, v68, v69
	v_cvt_pk_bf16_f32 v64, v112, v113
	v_cvt_pk_bf16_f32 v67, v70, v71
	v_cvt_pk_bf16_f32 v65, v114, v115
	v_exp_f32_e32 v93, v93
	v_exp_f32_e32 v94, v94
	v_mfma_f32_32x32x16_bf16 v[16:31], v[108:111], v[64:67], v[16:31]
	v_exp_f32_e32 v95, v95
	v_exp_f32_e32 v72, v72
	v_exp_f32_e32 v73, v73
	v_exp_f32_e32 v74, v74
	v_exp_f32_e32 v75, v75
	v_exp_f32_e32 v76, v76
	v_exp_f32_e32 v77, v77
	v_mfma_f32_32x32x16_bf16 v[0:15], v[104:107], v[64:67], v[0:15]
	v_exp_f32_e32 v78, v78
	v_exp_f32_e32 v79, v79
	v_cvt_pk_bf16_f32 v116, v88, v89
	v_cvt_pk_bf16_f32 v117, v90, v91
	v_cvt_pk_bf16_f32 v118, v92, v93
	v_cvt_pk_bf16_f32 v119, v94, v95
	s_waitcnt lgkmcnt(0)
	s_barrier
	v_mfma_f32_32x32x16_bf16 v[48:63], v[96:99], v[116:119], v[48:63]
	v_mfma_f32_32x32x16_bf16 v[32:47], v[100:103], v[116:119], v[32:47]
	v_cvt_pk_bf16_f32 v116, v72, v73
	v_cvt_pk_bf16_f32 v117, v74, v75
	v_cvt_pk_bf16_f32 v118, v76, v77
	v_cvt_pk_bf16_f32 v119, v78, v79
	s_nop 1
	v_mfma_f32_32x32x16_bf16 v[16:31], v[96:99], v[116:119], v[16:31]
	v_mfma_f32_32x32x16_bf16 v[0:15], v[100:103], v[116:119], v[0:15]
	s_cbranch_scc1 .LBB0_105
	s_cmp_lg_u32 s34, 1
	s_mov_b64 s[4:5], -1
	s_cbranch_scc0 .LBB0_103
	s_cmp_eq_u32 s34, 2
	s_cselect_b32 s84, s45, 0xa00
	s_mov_b64 s[4:5], 0
	s_mov_b64 s[8:9], s[84:85]
